# GLA prep: 32-row log-decay cumsum rewritten as a compact loop (hw exp2/log2 for logsigmoid); DeltaNet scan prefetch via SGPR base, staging writes moved off the step top
# speedup vs baseline: 1.5496x; 1.0296x over previous
.LBB0_475:
	s_and_b64 vcc, exec, s[0:1]
	s_cbranch_vccz .LBB0_497
	v_readlane_b32 s0, v252, 42
	s_mov_b32 s4, s0
	s_ashr_i32 s5, s0, 31
	s_lshl_b32 s2, s0, 5
	s_lshl_b64 s[18:19], s[4:5], 12
	v_readlane_b32 s24, v250, 5
	s_mul_i32 s14, s30, 0x81
	s_add_u32 s4, s24, s18
	v_readlane_b32 s25, v250, 7
	v_readlane_b32 s1, v252, 43
	s_addc_u32 s5, s25, s19
	s_lshl_b32 s6, s14, 14
	v_writelane_b32 v252, s0, 42
	s_ashr_i32 s3, s2, 31
	s_add_i32 s10, s6, 0x8000
	v_writelane_b32 v252, s1, 43
	s_add_u32 s0, s24, s10
	s_addc_u32 s1, s25, 0
	s_add_u32 s0, s0, s18
	s_addc_u32 s1, s1, s19
	v_readlane_b32 s34, v251, 63
	v_readlane_b32 s35, v250, 0
	s_add_u32 s8, s34, s10
	s_addc_u32 s9, s35, 0
	s_add_u32 s10, s56, s10
	s_mul_i32 s12, s30, 0x204000
	s_addc_u32 s11, s57, 0
	s_add_i32 s16, s12, 0x4000
	s_add_u32 s12, s24, s16
	s_addc_u32 s13, s25, 0
	s_add_u32 s12, s12, s18
	s_addc_u32 s13, s13, s19
	s_add_u32 s20, s34, s16
	s_addc_u32 s21, s35, 0
	s_add_u32 s22, s56, s16
	s_addc_u32 s23, s57, 0
	s_lshl_b32 s33, s14, 2
	v_readlane_b32 s36, v250, 3
	v_readlane_b32 s37, v250, 4
	s_add_u32 s16, s36, s33
	s_addc_u32 s17, s37, 0
	s_add_u32 s24, s24, s6
	s_addc_u32 s25, s25, 0
	s_add_u32 s24, s24, s18
	s_addc_u32 s25, s25, s19
	s_add_u32 s26, s34, s6
	s_addc_u32 s27, s35, 0
	v_mov_b32_e32 v0, v218
	s_add_u32 s18, s56, s6
	s_addc_u32 s19, s57, 0
	v_ashrrev_i32_e32 v1, 31, v0
	s_waitcnt vmcnt(3)
	v_lshlrev_b64 v[2:3], 4, v[0:1]
	v_lshl_add_u64 v[4:5], s[18:19], 0, v[2:3]
	s_movk_i32 s18, 0x2000
	s_waitcnt vmcnt(2)
	v_add_co_u32_e32 v6, vcc, s18, v4
	s_movk_i32 s19, 0x3000
	s_nop 0
	v_addc_co_u32_e32 v7, vcc, 0, v5, vcc
	s_waitcnt lgkmcnt(0)
	global_load_dwordx4 v[32:35], v[6:7], off offset:-4096
	global_load_dwordx4 v[36:39], v[6:7], off
	v_add_co_u32_e32 v6, vcc, s19, v4
	v_mov_b32_e32 v1, s33
	s_nop 0
	v_addc_co_u32_e32 v7, vcc, 0, v5, vcc
	global_load_dwordx4 v[64:67], v[4:5], off
	global_load_dwordx4 v[40:43], v[6:7], off
	v_lshl_add_u64 v[4:5], s[26:27], 0, v[2:3]
	v_add_co_u32_e32 v6, vcc, s18, v4
	s_waitcnt vmcnt(5)
	v_lshlrev_b32_e32 v11, 4, v0
	v_addc_co_u32_e32 v7, vcc, 0, v5, vcc
	global_load_dwordx4 v[48:51], v[6:7], off offset:-4096
	global_load_dwordx4 v[52:55], v[6:7], off
	v_add_co_u32_e32 v6, vcc, s19, v4
	s_movk_i32 s6, 0x110
	s_nop 0
	v_addc_co_u32_e32 v7, vcc, 0, v5, vcc
	global_load_dwordx4 v[44:47], v[4:5], off
	global_load_dwordx4 v[68:71], v[6:7], off
	v_lshl_add_u64 v[4:5], s[24:25], 0, v[2:3]
	v_lshl_add_u64 v[6:7], s[22:23], 0, v[2:3]
	global_load_dwordx4 v[82:85], v[4:5], off
	global_load_dwordx4 v[94:97], v[6:7], off
	v_add_co_u32_e32 v4, vcc, s18, v6
	v_ashrrev_i32_e32 v9, 6, v0
	s_nop 0
	v_addc_co_u32_e32 v5, vcc, 0, v7, vcc
	global_load_dwordx4 v[56:59], v[4:5], off offset:-4096
	global_load_dwordx4 v[60:63], v[4:5], off
	v_add_co_u32_e32 v4, vcc, s19, v6
	v_and_b32_e32 v145, 31, v0
	s_nop 0
	v_addc_co_u32_e32 v5, vcc, 0, v7, vcc
	v_lshl_add_u64 v[6:7], s[20:21], 0, v[2:3]
	global_load_dwordx4 v[72:75], v[4:5], off
	global_load_dwordx4 v[76:79], v[6:7], off
	v_add_co_u32_e32 v4, vcc, s18, v6
	v_bfe_u32 v10, v0, 5, 1
	s_nop 0
	v_addc_co_u32_e32 v5, vcc, 0, v7, vcc
	global_load_dwordx4 v[86:89], v[4:5], off offset:-4096
	global_load_dwordx4 v[90:93], v[4:5], off
	v_add_co_u32_e32 v4, vcc, s19, v6
	v_and_b32_e32 v8, 63, v0
	s_nop 0
	v_addc_co_u32_e32 v5, vcc, 0, v7, vcc
	v_lshl_add_u64 v[6:7], s[12:13], 0, v[2:3]
	global_load_dwordx4 v[106:109], v[4:5], off
	global_load_dwordx4 v[110:113], v[6:7], off
	v_lshl_add_u64 v[4:5], s[10:11], 0, v[2:3]
	v_add_co_u32_e32 v6, vcc, s18, v4
	global_load_dwordx3 v[142:144], v1, s[36:37]
	global_load_dwordx4 v[130:133], v[4:5], off
	v_addc_co_u32_e32 v7, vcc, 0, v5, vcc
	v_add_co_u32_e32 v4, vcc, s19, v4
	global_load_dwordx4 v[98:101], v[6:7], off offset:-4096
	global_load_dwordx4 v[102:105], v[6:7], off
	v_addc_co_u32_e32 v5, vcc, 0, v5, vcc
	v_lshl_add_u64 v[6:7], s[8:9], 0, v[2:3]
	global_load_dwordx4 v[114:117], v[4:5], off
	global_load_dwordx4 v[118:121], v[6:7], off
	v_add_co_u32_e32 v4, vcc, s18, v6
	v_add_u32_e32 v1, 0x100, v0
	s_nop 0
	v_addc_co_u32_e32 v5, vcc, 0, v7, vcc
	global_load_dwordx4 v[122:125], v[4:5], off offset:-4096
	global_load_dwordx4 v[126:129], v[4:5], off
	v_add_co_u32_e32 v4, vcc, s19, v6
	s_movk_i32 s8, 0x90
	s_nop 0
	v_addc_co_u32_e32 v5, vcc, 0, v7, vcc
	v_lshl_add_u64 v[6:7], s[0:1], 0, v[2:3]
	global_load_dwordx4 v[134:137], v[4:5], off
	global_load_dwordx4 v[138:141], v[6:7], off
	v_add_u32_e32 v5, 0x200, v0
	v_lshrrev_b32_e32 v7, 4, v0
	v_and_b32_e32 v4, 0xf0, v11
	v_mad_u64_u32 v[146:147], s[0:1], v7, s6, v[4:5]
	v_lshrrev_b32_e32 v7, 4, v1
	v_add_u32_e32 v6, 0x300, v0
	v_mad_u64_u32 v[148:149], s[0:1], v7, s6, v[4:5]
	v_lshrrev_b32_e32 v7, 4, v5
	v_mad_u64_u32 v[150:151], s[0:1], v7, s6, v[4:5]
	v_lshrrev_b32_e32 v7, 4, v6
	v_mad_u64_u32 v[152:153], s[0:1], v7, s6, v[4:5]
	v_and_b32_e32 v4, 0x70, v11
	v_lshrrev_b32_e32 v1, 3, v1
	v_lshrrev_b32_e32 v7, 3, v0
	v_mad_u64_u32 v[156:157], s[0:1], v1, s8, v[4:5]
	v_lshrrev_b32_e32 v1, 3, v5
	v_mad_u64_u32 v[154:155], s[0:1], v7, s8, v[4:5]
	v_mad_u64_u32 v[158:159], s[0:1], v1, s8, v[4:5]
	v_lshrrev_b32_e32 v1, 3, v6
	v_lshlrev_b32_e32 v7, 5, v9
	v_mad_u64_u32 v[160:161], s[0:1], v1, s8, v[4:5]
	v_and_b32_e32 v4, 0xffffffc0, v0
	v_or_b32_e32 v11, v7, v145
	v_and_or_b32 v7, v7, 32, v145
	v_lshlrev_b32_e32 v171, 12, v9
	v_lshlrev_b32_e32 v172, 9, v10
	v_mul_u32_u24_e32 v1, 0x110, v145
	v_mad_u32_u24 v5, v145, s6, v4
	v_lshlrev_b32_e32 v147, 4, v10
	v_mul_u32_u24_e32 v7, 0x110, v7
	v_and_b32_e32 v0, 0xffffff80, v0
	v_lshl_add_u64 v[166:167], s[4:5], 0, v[2:3]
	s_mul_i32 s6, s30, 0x2b0000
	s_lshl_b64 s[4:5], s[2:3], 2
	v_add3_u32 v149, v7, v0, v147
	v_add3_u32 v151, v1, v0, v147
	s_add_u32 s4, s6, s4
	v_or_b32_e32 v0, v171, v172
	s_addc_u32 s5, 0, s5
	v_ashrrev_i32_e32 v1, 31, v0
	v_lshlrev_b32_e32 v6, 3, v10
	v_lshl_add_u64 v[0:1], v[0:1], 2, s[4:5]
	v_readlane_b32 s40, v252, 13
	v_mul_lo_u32 v11, v11, s8
	v_or_b32_e32 v4, v4, v6
	v_lshlrev_b32_e32 v153, 4, v8
	v_mul_u32_u24_e32 v155, 0x90, v145
	v_and_b32_e32 v7, 0x1000, v171
	v_lshl_or_b32 v0, v145, 2, v0
	v_readlane_b32 s54, v252, 27
	v_readlane_b32 s55, v252, 28
	v_mov_b32_e32 v157, 0
	s_mov_b32 s15, 5
	s_mov_b32 s7, 0
	v_cmp_gt_i32_e32 vcc, 2, v9
	v_cmp_lt_i32_e64 s[0:1], 1, v9
	v_lshl_add_u64 v[162:163], s[56:57], 0, v[2:3]
	v_lshl_add_u64 v[164:165], s[34:35], 0, v[2:3]
	v_lshl_add_u64 v[168:169], s[54:55], 0, v[0:1]
	s_mov_b64 s[8:9], 0
	s_movk_i32 s3, 0x7fff
	s_mov_b32 s12, 0x7060302
	v_add_u32_e32 v159, v5, v6
	v_add_u32_e32 v161, v11, v147
	v_mov_b32_e32 v173, 1
	v_add_u32_e32 v174, v4, v155
	v_add_u32_e32 v175, v153, v7
	v_mov_b32_e32 v0, 0
	v_mov_b32_e32 v1, v157
	v_mov_b32_e32 v2, v157
	v_mov_b32_e32 v3, v157
	v_mov_b32_e32 v4, v157
	v_mov_b32_e32 v5, v157
	v_mov_b32_e32 v6, v157
	v_mov_b32_e32 v7, v157
	v_mov_b32_e32 v8, v157
	v_mov_b32_e32 v9, v157
	v_mov_b32_e32 v10, v157
	v_mov_b32_e32 v11, v157
	v_mov_b32_e32 v12, v157
	v_mov_b32_e32 v13, v157
	s_waitcnt vmcnt(28)
	v_mov_b32_e32 v14, v157
	v_mov_b32_e32 v15, v157
	s_barrier
	v_readlane_b32 s41, v252, 14
	v_readlane_b32 s42, v252, 15
	v_readlane_b32 s43, v252, 16
	v_readlane_b32 s44, v252, 17
	v_readlane_b32 s45, v252, 18
	v_readlane_b32 s46, v252, 19
	v_readlane_b32 s47, v252, 20
	v_readlane_b32 s48, v252, 21
	v_readlane_b32 s49, v252, 22
	v_readlane_b32 s50, v252, 23
	v_readlane_b32 s51, v252, 24
	v_readlane_b32 s52, v252, 25
	v_readlane_b32 s53, v252, 26
	v_readlane_b32 s98, v252, 0
	v_readlane_b32 s99, v252, 1
	s_nop 1
	v_subrev_u32_e32 v188, s98, v162
	v_subrev_u32_e32 v192, s98, v164
	v_subrev_u32_e32 v196, s98, v166
	v_add_u32_e32 v189, 0x1000, v188
	v_add_u32_e32 v193, 0x1000, v192
	v_add_u32_e32 v190, 0x2000, v188
	v_add_u32_e32 v194, 0x2000, v192
	v_add_u32_e32 v191, 0x3000, v188
	v_add_u32_e32 v195, 0x3000, v192
	s_waitcnt vmcnt(20)
	ds_write_b128 v146, v[64:67] offset:24576
	ds_write_b128 v148, v[32:35] offset:24576
	ds_write_b128 v150, v[36:39] offset:24576
	ds_write_b128 v152, v[40:43] offset:24576
	ds_write_b128 v154, v[44:47] offset:41984
	ds_write_b128 v156, v[48:51] offset:41984
	ds_write_b128 v158, v[52:55] offset:41984
	ds_write_b128 v160, v[68:71] offset:41984
	ds_write_b128 v154, v[82:85] offset:60416
	s_branch .LBB0_478
.LBB0_477:
	s_or_b64 exec, exec, s[4:5]
	s_waitcnt vmcnt(10)
	ds_write_b128 v146, v[64:67] offset:24576
	ds_write_b128 v148, v[32:35] offset:24576
	ds_write_b128 v150, v[36:39] offset:24576
	ds_write_b128 v152, v[40:43] offset:24576
	ds_write_b128 v154, v[44:47] offset:41984
	ds_write_b128 v156, v[48:51] offset:41984
	ds_write_b128 v158, v[52:55] offset:41984
	ds_write_b128 v160, v[68:71] offset:41984
	ds_write_b128 v154, v[82:85] offset:60416
	s_waitcnt lgkmcnt(0)
	s_barrier
	s_nop 1
	ds_read_b128 v[16:19], v178 offset:8704
	ds_read_b128 v[20:23], v178 offset:8736
	ds_read_b128 v[24:27], v178 offset:8768
	ds_read_b128 v[28:31], v178 offset:8800
	v_pk_mul_f32 v[14:15], v[144:145], v[14:15] op_sel_hi:[0,1]
	v_pk_mul_f32 v[12:13], v[144:145], v[12:13] op_sel_hi:[0,1]
	v_pk_mul_f32 v[10:11], v[144:145], v[10:11] op_sel_hi:[0,1]
	v_pk_mul_f32 v[8:9], v[144:145], v[8:9] op_sel_hi:[0,1]
	v_pk_mul_f32 v[6:7], v[144:145], v[6:7] op_sel_hi:[0,1]
	v_pk_mul_f32 v[4:5], v[144:145], v[4:5] op_sel_hi:[0,1]
	v_pk_mul_f32 v[2:3], v[144:145], v[2:3] op_sel_hi:[0,1]
	v_pk_mul_f32 v[0:1], v[144:145], v[0:1] op_sel_hi:[0,1]
	s_waitcnt lgkmcnt(3)
	s_nop 0
	v_mfma_f32_32x32x16_bf16 v[0:15], v[118:121], v[16:19], v[0:15]
	s_waitcnt lgkmcnt(2)
	v_mfma_f32_32x32x16_bf16 v[0:15], v[114:117], v[20:23], v[0:15]
	s_waitcnt lgkmcnt(1)
	v_mfma_f32_32x32x16_bf16 v[0:15], v[102:105], v[24:27], v[0:15]
	s_waitcnt lgkmcnt(0)
	v_mfma_f32_32x32x16_bf16 v[0:15], v[98:101], v[28:31], v[0:15]
	s_and_b64 s[4:5], s[10:11], exec
	s_cselect_b32 s10, 0x80, s15
	s_add_i32 s6, s10, s14
	s_lshl_b64 s[20:21], s[6:7], 14
	s_add_u32 s100, s98, s20
	s_addc_u32 s101, s99, s21
	global_load_dwordx4 v[98:101], v189, s[100:101]
	global_load_dwordx4 v[102:105], v190, s[100:101]
	s_ashr_i32 s11, s10, 31
	global_load_dwordx4 v[114:117], v191, s[100:101]
	global_load_dwordx4 v[118:121], v192, s[100:101]
	global_load_dwordx4 v[122:125], v193, s[100:101]
	global_load_dwordx4 v[126:129], v194, s[100:101]
	s_lshl_b64 s[4:5], s[10:11], 2
	s_add_u32 s4, s16, s4
	global_load_dwordx4 v[134:137], v195, s[100:101]
	global_load_dwordx4 v[138:141], v196, s[100:101]
	s_addc_u32 s5, s17, s5
	global_load_dwordx4 v[130:133], v188, s[100:101]
	global_load_dword v144, v157, s[4:5]
	s_add_u32 s8, s8, 0x10000
	s_addc_u32 s9, s9, 0
	s_add_i32 s15, s15, 3
	s_cmp_lg_u32 s8, 0x2b0000
	s_waitcnt vmcnt(20)
	v_mov_b32_e32 v142, v177
	s_cbranch_scc0 .LBB0_496
.LBB0_478:
	v_lshl_add_u64 v[16:17], v[168:169], 0, s[8:9]
	s_mov_b32 s4, 0x7489000
	v_add_co_u32_e64 v18, s[4:5], s4, v16
	v_add_u32_e32 v179, 0xe800, v174
	s_nop 0
	v_addc_co_u32_e64 v19, s[4:5], 0, v17, s[4:5]
	s_mov_b32 s4, 0x748a000
	s_nop 0
	v_add_co_u32_e64 v20, s[4:5], s4, v16
	s_nop 1
	v_addc_co_u32_e64 v21, s[4:5], 0, v17, s[4:5]
	s_mov_b32 s4, 0x748b000
	global_store_dword v[20:21], v0, off offset:-4096 nt
	global_store_dword v[18:19], v1, off offset:512 nt
	global_store_dword v[18:19], v2, off offset:1024 nt
	global_store_dword v[18:19], v3, off offset:1536 nt
	global_store_dword v[20:21], v4, off nt
	global_store_dword v[20:21], v5, off offset:512 nt
	global_store_dword v[20:21], v6, off offset:1024 nt
	global_store_dword v[20:21], v7, off offset:1536 nt
	v_add_co_u32_e64 v18, s[4:5], s4, v16
	s_nop 0
	v_addc_co_u32_e64 v19, s[4:5], 0, v17, s[4:5]
	s_mov_b32 s4, 0x748c000
	s_nop 0
	v_add_co_u32_e64 v16, s[4:5], s4, v16
	s_nop 0
	v_addc_co_u32_e64 v17, s[4:5], 0, v17, s[4:5]
	global_store_dword v[16:17], v8, off offset:-4096 nt
	global_store_dword v[18:19], v9, off offset:512 nt
	global_store_dword v[18:19], v10, off offset:1024 nt
	global_store_dword v[18:19], v11, off offset:1536 nt
	global_store_dword v[16:17], v12, off nt
	global_store_dword v[16:17], v13, off offset:512 nt
	global_store_dword v[16:17], v14, off offset:1024 nt
	global_store_dword v[16:17], v15, off offset:1536 nt
	v_cvt_pk_bf16_f32 v16, v0, v1
	v_cvt_pk_bf16_f32 v17, v2, v3
	v_cvt_pk_bf16_f32 v18, v4, v5
	v_cvt_pk_bf16_f32 v19, v6, v7
	ds_write2_b64 v159, v[16:17], v[18:19] offset1:2
	v_cvt_pk_bf16_f32 v16, v8, v9
	v_cvt_pk_bf16_f32 v17, v10, v11
	v_cvt_pk_bf16_f32 v18, v12, v13
	v_cvt_pk_bf16_f32 v19, v14, v15
	ds_write2_b64 v159, v[16:17], v[18:19] offset0:4 offset1:6
	s_waitcnt lgkmcnt(0)
	s_barrier
	ds_read_b128 v[44:47], v161 offset:41984
	ds_read_b128 v[40:43], v161 offset:42016
	ds_read_b128 v[36:39], v161 offset:42048
	ds_read_b128 v[32:35], v161 offset:42080
	s_and_saveexec_b64 s[4:5], vcc
	s_cbranch_execz .LBB0_480
	ds_read2_b64 v[52:55], v179 offset0:128 offset1:130
	ds_read2_b64 v[48:51], v179 offset0:132 offset1:134

.LBB0_484:
	s_or_b64 exec, exec, s[4:5]
	s_waitcnt vmcnt(26)
	ds_write_b128 v146, v[94:97] offset:24576
	ds_write_b128 v148, v[56:59] offset:24576
	ds_write_b128 v150, v[60:63] offset:24576
	ds_write_b128 v152, v[72:75] offset:24576
	ds_write_b128 v154, v[76:79] offset:41984
	ds_write_b128 v156, v[86:89] offset:41984
	ds_write_b128 v158, v[90:93] offset:41984
	ds_write_b128 v160, v[106:109] offset:41984
	ds_write_b128 v154, v[110:113] offset:60416
	v_add_u32_e32 v178, v147, v155
	s_waitcnt lgkmcnt(0)
	s_barrier
	ds_read_b128 v[16:19], v178 offset:8704
	ds_read_b128 v[20:23], v178 offset:8736
	ds_read_b128 v[24:27], v178 offset:8768
	ds_read_b128 v[28:31], v178 offset:8800
	s_waitcnt vmcnt(25)
	v_pk_mul_f32 v[14:15], v[14:15], v[142:143] op_sel_hi:[1,0]
	v_pk_mul_f32 v[12:13], v[12:13], v[142:143] op_sel_hi:[1,0]
	v_pk_mul_f32 v[10:11], v[10:11], v[142:143] op_sel_hi:[1,0]
	v_pk_mul_f32 v[8:9], v[8:9], v[142:143] op_sel_hi:[1,0]
	v_pk_mul_f32 v[6:7], v[6:7], v[142:143] op_sel_hi:[1,0]
	v_pk_mul_f32 v[4:5], v[4:5], v[142:143] op_sel_hi:[1,0]
	v_pk_mul_f32 v[2:3], v[2:3], v[142:143] op_sel_hi:[1,0]
	v_pk_mul_f32 v[0:1], v[0:1], v[142:143] op_sel_hi:[1,0]
	s_waitcnt lgkmcnt(3)
	s_nop 0
	v_mfma_f32_32x32x16_bf16 v[0:15], v[44:47], v[16:19], v[0:15]
	s_waitcnt lgkmcnt(2)
	v_mfma_f32_32x32x16_bf16 v[0:15], v[40:43], v[20:23], v[0:15]
	s_waitcnt lgkmcnt(1)
	v_mfma_f32_32x32x16_bf16 v[0:15], v[36:39], v[24:27], v[0:15]
	s_waitcnt lgkmcnt(0)
	v_mfma_f32_32x32x16_bf16 v[0:15], v[32:35], v[28:31], v[0:15]
	s_add_i32 s6, s15, -2
	s_cmp_eq_u32 s8, 0x2a0000
	s_cselect_b64 s[10:11], -1, 0
	s_and_b64 s[4:5], s[10:11], exec
	s_cselect_b32 s20, 0x80, s6
	s_add_i32 s6, s20, s14
	s_lshl_b64 s[22:23], s[6:7], 14
	s_add_u32 s100, s98, s22
	s_addc_u32 s101, s99, s23
	global_load_dwordx4 v[32:35], v189, s[100:101]
	global_load_dwordx4 v[36:39], v190, s[100:101]
	s_ashr_i32 s21, s20, 31
	global_load_dwordx4 v[40:43], v191, s[100:101]
	global_load_dwordx4 v[44:47], v192, s[100:101]
	global_load_dwordx4 v[48:51], v193, s[100:101]
	global_load_dwordx4 v[52:55], v194, s[100:101]
	s_lshl_b64 s[4:5], s[20:21], 2
	s_add_u32 s4, s16, s4
	global_load_dwordx4 v[68:71], v195, s[100:101]
	global_load_dwordx4 v[82:85], v196, s[100:101]
	s_addc_u32 s5, s17, s5
	global_load_dwordx4 v[64:67], v188, s[100:101]
	global_load_dword v177, v157, s[4:5]
	v_cvt_pk_bf16_f32 v16, v0, v1
	v_cvt_pk_bf16_f32 v17, v2, v3
	v_cvt_pk_bf16_f32 v18, v4, v5
	v_cvt_pk_bf16_f32 v19, v6, v7
	ds_write2_b64 v159, v[16:17], v[18:19] offset1:2
	v_cvt_pk_bf16_f32 v16, v8, v9
	v_cvt_pk_bf16_f32 v17, v10, v11
	v_cvt_pk_bf16_f32 v18, v12, v13
	v_cvt_pk_bf16_f32 v19, v14, v15
	ds_write2_b64 v159, v[16:17], v[18:19] offset0:4 offset1:6
	s_waitcnt lgkmcnt(0)
	s_barrier
	ds_read_b128 v[76:79], v161 offset:41984
	ds_read_b128 v[72:75], v161 offset:42016
	ds_read_b128 v[60:63], v161 offset:42048
	ds_read_b128 v[56:59], v161 offset:42080
	s_and_saveexec_b64 s[4:5], vcc
	s_cbranch_execz .LBB0_486
	ds_read2_b64 v[90:93], v179 offset0:128 offset1:130
	ds_read2_b64 v[86:89], v179 offset0:132 offset1:134

.LBB0_490:
	s_or_b64 exec, exec, s[4:5]
	s_waitcnt vmcnt(26)
	ds_write_b128 v146, v[130:133] offset:24576
	ds_write_b128 v148, v[98:101] offset:24576
	ds_write_b128 v150, v[102:105] offset:24576
	ds_write_b128 v152, v[114:117] offset:24576
	ds_write_b128 v154, v[118:121] offset:41984
	ds_write_b128 v156, v[122:125] offset:41984
	ds_write_b128 v158, v[126:129] offset:41984
	ds_write_b128 v160, v[134:137] offset:41984
	ds_write_b128 v154, v[138:141] offset:60416
	s_waitcnt lgkmcnt(0)
	s_barrier
	s_nop 1
	ds_read_b128 v[16:19], v178 offset:8704
	ds_read_b128 v[20:23], v178 offset:8736
	ds_read_b128 v[24:27], v178 offset:8768
	ds_read_b128 v[28:31], v178 offset:8800
	v_pk_mul_f32 v[0:1], v[142:143], v[0:1] op_sel:[1,0]
	v_pk_mul_f32 v[14:15], v[142:143], v[14:15] op_sel:[1,0]
	v_pk_mul_f32 v[12:13], v[142:143], v[12:13] op_sel:[1,0]
	v_pk_mul_f32 v[10:11], v[142:143], v[10:11] op_sel:[1,0]
	v_pk_mul_f32 v[8:9], v[142:143], v[8:9] op_sel:[1,0]
	v_pk_mul_f32 v[6:7], v[142:143], v[6:7] op_sel:[1,0]
	v_pk_mul_f32 v[4:5], v[142:143], v[4:5] op_sel:[1,0]
	v_pk_mul_f32 v[2:3], v[142:143], v[2:3] op_sel:[1,0]
	s_waitcnt lgkmcnt(3)
	s_nop 0
	v_mfma_f32_32x32x16_bf16 v[0:15], v[76:79], v[16:19], v[0:15]
	s_waitcnt lgkmcnt(2)
	v_mfma_f32_32x32x16_bf16 v[0:15], v[72:75], v[20:23], v[0:15]
	s_waitcnt lgkmcnt(1)
	v_mfma_f32_32x32x16_bf16 v[0:15], v[60:63], v[24:27], v[0:15]
	s_waitcnt lgkmcnt(0)
	v_mfma_f32_32x32x16_bf16 v[0:15], v[56:59], v[28:31], v[0:15]
	s_add_i32 s6, s15, -1
	s_and_b64 s[4:5], s[10:11], exec
	s_cselect_b32 s20, 0x80, s6
	s_add_i32 s6, s20, s14
	s_lshl_b64 s[22:23], s[6:7], 14
	s_add_u32 s100, s98, s22
	s_addc_u32 s101, s99, s23
	global_load_dwordx4 v[56:59], v189, s[100:101]
	global_load_dwordx4 v[60:63], v190, s[100:101]
	s_ashr_i32 s21, s20, 31
	global_load_dwordx4 v[72:75], v191, s[100:101]
	global_load_dwordx4 v[76:79], v192, s[100:101]
	global_load_dwordx4 v[86:89], v193, s[100:101]
	global_load_dwordx4 v[90:93], v194, s[100:101]
	s_lshl_b64 s[4:5], s[20:21], 2
	s_add_u32 s4, s16, s4
	global_load_dwordx4 v[106:109], v195, s[100:101]
	global_load_dwordx4 v[110:113], v196, s[100:101]
	s_addc_u32 s5, s17, s5
	global_load_dwordx4 v[94:97], v188, s[100:101]
	global_load_dword v143, v157, s[4:5]
	v_cvt_pk_bf16_f32 v16, v0, v1
	v_cvt_pk_bf16_f32 v17, v2, v3
	v_cvt_pk_bf16_f32 v18, v4, v5
	v_cvt_pk_bf16_f32 v19, v6, v7
	ds_write2_b64 v159, v[16:17], v[18:19] offset1:2
	v_cvt_pk_bf16_f32 v16, v8, v9
	v_cvt_pk_bf16_f32 v17, v10, v11
	v_cvt_pk_bf16_f32 v18, v12, v13
	v_cvt_pk_bf16_f32 v19, v14, v15
	ds_write2_b64 v159, v[16:17], v[18:19] offset0:4 offset1:6
	s_waitcnt lgkmcnt(0)
	s_barrier
	ds_read_b128 v[118:121], v161 offset:41984
	ds_read_b128 v[114:117], v161 offset:42016
	ds_read_b128 v[102:105], v161 offset:42048
	ds_read_b128 v[98:101], v161 offset:42080
	s_and_saveexec_b64 s[4:5], vcc
	s_cbranch_execz .LBB0_492
	ds_read2_b64 v[126:129], v179 offset0:128 offset1:130
	ds_read2_b64 v[122:125], v179 offset0:132 offset1:134

.LBB0_1932:
	s_or_b64 exec, exec, s[12:13]
	v_cmp_lt_i32_e32 vcc, s16, v1
	s_waitcnt vmcnt(3)
	v_lshlrev_b32_e32 v12, 2, v0
	s_lshl_b32 s1, s1, 7
	s_waitcnt vmcnt(2)
	v_cndmask_b32_e32 v1, 0, v4, vcc
	v_cmp_lt_i32_e32 vcc, s16, v5
	s_waitcnt vmcnt(0)
	ds_write2st64_b32 v12, v10, v1 offset1:4
	s_and_b32 s33, s1, 0x180
	v_cndmask_b32_e32 v1, 0, v7, vcc
	v_cmp_lt_i32_e32 vcc, s16, v8
	v_readlane_b32 s40, v252, 13
	v_readlane_b32 s41, v252, 14
	v_cndmask_b32_e32 v2, 0, v9, vcc
	ds_write2st64_b32 v12, v1, v2 offset0:8 offset1:12
	v_and_b32_e32 v1, 0x7f, v0
	v_or_b32_e32 v2, s33, v1
	v_readlane_b32 s42, v252, 15
	v_readlane_b32 s43, v252, 16
	v_readlane_b32 s44, v252, 17
	v_readlane_b32 s45, v252, 18
	v_lshlrev_b32_e32 v16, 2, v2
	v_readlane_b32 s46, v252, 19
	v_readlane_b32 s47, v252, 20
	v_readlane_b32 s48, v252, 21
	v_readlane_b32 s49, v252, 22
	s_mov_b64 s[40:41], s[44:45]
	v_lshl_add_u64 v[10:11], s[40:41], 0, v[16:17]
	s_movk_i32 s1, 0x1000
	v_add_co_u32_e32 v2, vcc, s1, v10
	s_movk_i32 s1, 0x2000
	s_nop 0
	v_addc_co_u32_e32 v3, vcc, 0, v11, vcc
	v_add_co_u32_e32 v4, vcc, s1, v10
	s_movk_i32 s1, 0x3000
	s_nop 0
	v_addc_co_u32_e32 v5, vcc, 0, v11, vcc
	s_waitcnt lgkmcnt(0)
	s_barrier
	global_load_dword v14, v16, s[40:41]
	global_load_dword v15, v16, s[40:41] offset:2048
	global_load_dword v23, v[4:5], off offset:-4096
	global_load_dword v24, v[2:3], off offset:2048
	global_load_dword v25, v[4:5], off
	global_load_dword v26, v[4:5], off offset:2048
	v_add_co_u32_e32 v2, vcc, s1, v10
	s_movk_i32 s1, 0x4000
	s_nop 0
	v_addc_co_u32_e32 v3, vcc, 0, v11, vcc
	v_add_co_u32_e32 v4, vcc, s1, v10
	s_movk_i32 s1, 0x5000
	s_nop 0
	v_addc_co_u32_e32 v5, vcc, 0, v11, vcc
	v_add_co_u32_e32 v6, vcc, s1, v10
	global_load_dword v8, v[4:5], off offset:-4096
	global_load_dword v9, v[2:3], off offset:2048
	s_nop 0
	global_load_dword v2, v[4:5], off
	global_load_dword v3, v[4:5], off offset:2048
	v_addc_co_u32_e32 v7, vcc, 0, v11, vcc
	v_add_co_u32_e32 v28, vcc, 0x6000, v10
	global_load_dword v4, v[6:7], off
	global_load_dword v5, v[6:7], off offset:2048
	v_addc_co_u32_e32 v29, vcc, 0, v11, vcc
	global_load_dword v6, v[28:29], off
	global_load_dword v7, v[28:29], off offset:2048
	v_add_co_u32_e32 v28, vcc, 0x7000, v10
	s_mov_b64 s[42:43], s[46:47]
	s_nop 0
	v_addc_co_u32_e32 v29, vcc, 0, v11, vcc
	global_load_dword v10, v[28:29], off
	global_load_dword v11, v[28:29], off offset:2048
	v_ashrrev_i32_e32 v13, 7, v0
	global_load_dword v16, v16, s[42:43]
	v_lshlrev_b32_e32 v22, 5, v13
	v_mov_b32_e32 v27, 0
	v_cmp_lt_i32_e32 vcc, s16, v22
	v_mov_b32_e32 v28, 0
	v_readlane_b32 s50, v252, 23
	v_readlane_b32 s51, v252, 24
	v_readlane_b32 s52, v252, 25
	v_readlane_b32 s53, v252, 26
	v_readlane_b32 s54, v252, 27
	v_readlane_b32 s55, v252, 28
	s_mov_b64 s[44:45], s[48:49]
	s_waitcnt vmcnt(0)
	v_lshlrev_b32_e32 v1, 2, v1
	v_mov_b32_e32 v29, v22
	v_lshlrev_b32_e32 v18, 11, v13
	v_mov_b32_e32 v28, 0
	s_mov_b32 s12, 0x3fb8aa3b
	s_mov_b32 s1, 0
	v_lshl_or_b32 v19, v29, 9, v1
.Lglaprep_row:
	ds_read_b128 v[30:33], v18
	ds_read_b128 v[34:37], v18 offset:16
	ds_read_b128 v[38:41], v18 offset:32
	ds_read_b128 v[42:45], v18 offset:48
	v_cmp_lt_i32_e32 vcc, s16, v29
	s_waitcnt lgkmcnt(0)
	v_fma_f32 v27, v14, v30, v16
	v_fmac_f32_e32 v27, v15, v31
	v_fmac_f32_e32 v27, v23, v32
	v_fmac_f32_e32 v27, v24, v33
	v_fmac_f32_e32 v27, v25, v34
	v_fmac_f32_e32 v27, v26, v35
	v_fmac_f32_e32 v27, v8, v36
	v_fmac_f32_e32 v27, v9, v37
	v_fmac_f32_e32 v27, v2, v38
	v_fmac_f32_e32 v27, v3, v39
	v_fmac_f32_e32 v27, v4, v40
	v_fmac_f32_e32 v27, v5, v41
	v_fmac_f32_e32 v27, v6, v42
	v_fmac_f32_e32 v27, v7, v43
	v_fmac_f32_e32 v27, v10, v44
	v_fmac_f32_e32 v27, v11, v45
	v_mul_f32_e64 v20, -|v27|, s12
	v_exp_f32_e32 v20, v20
	v_min_f32_e32 v22, 0, v27
	v_add_f32_e32 v20, 1.0, v20
	v_log_f32_e32 v20, v20
	v_mul_f32_e32 v22, 0x3d800000, v22
	v_fmac_f32_e32 v22, 0xbd317218, v20
	v_cndmask_b32_e32 v22, 0, v22, vcc
	v_add_f32_e32 v28, v28, v22
	ds_write_b32 v19, v28 offset:4096
	v_add_u32_e32 v19, 0x200, v19
	v_add_u32_e32 v18, 64, v18
	v_add_u32_e32 v29, 1, v29
	s_add_i32 s1, s1, 1
	s_cmp_lt_u32 s1, 31
	s_cbranch_scc1 .Lglaprep_row
	ds_read_b128 v[30:33], v18
	ds_read_b128 v[34:37], v18 offset:16
	ds_read_b128 v[38:41], v18 offset:32
	ds_read_b128 v[42:45], v18 offset:48
	v_cmp_lt_i32_e32 vcc, s16, v29
	s_waitcnt lgkmcnt(0)
	v_fma_f32 v27, v14, v30, v16
	v_fmac_f32_e32 v27, v15, v31
	v_fmac_f32_e32 v27, v23, v32
	v_fmac_f32_e32 v27, v24, v33
	v_fmac_f32_e32 v27, v25, v34
	v_fmac_f32_e32 v27, v26, v35
	v_fmac_f32_e32 v27, v8, v36
	v_fmac_f32_e32 v27, v9, v37
	v_fmac_f32_e32 v27, v2, v38
	v_fmac_f32_e32 v27, v3, v39
	v_fmac_f32_e32 v27, v4, v40
	v_fmac_f32_e32 v27, v5, v41
	v_fmac_f32_e32 v27, v6, v42
	v_fmac_f32_e32 v27, v7, v43
	v_fmac_f32_e32 v27, v10, v44
	v_fmac_f32_e32 v27, v11, v45
	v_mul_f32_e64 v20, -|v27|, s12
	v_exp_f32_e32 v20, v20
	v_min_f32_e32 v22, 0, v27
	v_add_f32_e32 v20, 1.0, v20
	v_log_f32_e32 v20, v20
	v_mul_f32_e32 v22, 0x3d800000, v22
	v_fmac_f32_e32 v22, 0xbd317218, v20
	v_cndmask_b32_e32 v27, 0, v22, vcc
	v_mov_b32_e32 v18, 0x3f317218
	v_mov_b32_e32 v20, 0x3ecc95a3
	v_lshlrev_b32_e32 v22, 5, v13
	s_waitcnt vmcnt(8)
	v_add_f32_e32 v2, v28, v27
	s_waitcnt vmcnt(7)
	v_lshl_or_b32 v3, v29, 9, v1
	v_cmp_gt_u32_e32 vcc, s28, v0
	ds_write_b32 v3, v2 offset:4096
	s_and_saveexec_b64 s[12:13], vcc
	ds_write_b32 v1, v2 offset:36864
	s_or_b64 exec, exec, s[12:13]
	v_cmp_eq_u32_e32 vcc, 1, v13
	s_waitcnt lgkmcnt(0)
	s_barrier
	s_and_saveexec_b64 s[12:13], vcc
	s_cbranch_execz .LBB0_2000
	s_waitcnt vmcnt(6)
	ds_read_b32 v4, v1 offset:36864
	ds_read2st64_b32 v[2:3], v1 offset0:80 offset1:82
	s_waitcnt lgkmcnt(0)
	v_add_f32_e32 v2, v4, v2
	v_add_f32_e32 v3, v4, v3
	ds_write2st64_b32 v1, v2, v3 offset0:80 offset1:82
	ds_read2st64_b32 v[2:3], v1 offset0:84 offset1:86
	s_waitcnt lgkmcnt(0)
	v_add_f32_e32 v2, v4, v2
	v_add_f32_e32 v3, v4, v3
	ds_write2st64_b32 v1, v2, v3 offset0:84 offset1:86
	ds_read2st64_b32 v[2:3], v1 offset0:88 offset1:90
	s_waitcnt lgkmcnt(0)
	v_add_f32_e32 v2, v4, v2
	v_add_f32_e32 v3, v4, v3
	ds_write2st64_b32 v1, v2, v3 offset0:88 offset1:90
	ds_read2st64_b32 v[2:3], v1 offset0:92 offset1:94
	s_waitcnt lgkmcnt(0)
	v_add_f32_e32 v2, v4, v2
	v_add_f32_e32 v3, v4, v3
	ds_write2st64_b32 v1, v2, v3 offset0:92 offset1:94
	ds_read2st64_b32 v[2:3], v1 offset0:96 offset1:98
	s_waitcnt lgkmcnt(0)
	v_add_f32_e32 v2, v4, v2
	v_add_f32_e32 v3, v4, v3
	ds_write2st64_b32 v1, v2, v3 offset0:96 offset1:98
	ds_read2st64_b32 v[2:3], v1 offset0:100 offset1:102
	s_waitcnt lgkmcnt(0)
	v_add_f32_e32 v2, v4, v2
	v_add_f32_e32 v3, v4, v3
	ds_write2st64_b32 v1, v2, v3 offset0:100 offset1:102
	ds_read2st64_b32 v[2:3], v1 offset0:104 offset1:106
	s_waitcnt lgkmcnt(0)
	v_add_f32_e32 v2, v4, v2
	v_add_f32_e32 v3, v4, v3
	ds_write2st64_b32 v1, v2, v3 offset0:104 offset1:106
	ds_read2st64_b32 v[2:3], v1 offset0:108 offset1:110
	s_waitcnt lgkmcnt(0)
	v_add_f32_e32 v2, v4, v2
	v_add_f32_e32 v3, v4, v3
	ds_write2st64_b32 v1, v2, v3 offset0:108 offset1:110
	ds_read2st64_b32 v[2:3], v1 offset0:112 offset1:114
	s_waitcnt lgkmcnt(0)
	v_add_f32_e32 v2, v4, v2
	v_add_f32_e32 v3, v4, v3
	ds_write2st64_b32 v1, v2, v3 offset0:112 offset1:114
	ds_read2st64_b32 v[2:3], v1 offset0:116 offset1:118
	s_waitcnt lgkmcnt(0)
	v_add_f32_e32 v2, v4, v2
	v_add_f32_e32 v3, v4, v3
	ds_write2st64_b32 v1, v2, v3 offset0:116 offset1:118
	ds_read2st64_b32 v[2:3], v1 offset0:120 offset1:122
	s_waitcnt lgkmcnt(0)
	v_add_f32_e32 v2, v4, v2
	v_add_f32_e32 v3, v4, v3
	ds_write2st64_b32 v1, v2, v3 offset0:120 offset1:122
	ds_read2st64_b32 v[2:3], v1 offset0:124 offset1:126
	s_waitcnt lgkmcnt(0)
	v_add_f32_e32 v2, v4, v2
	v_add_f32_e32 v3, v4, v3
	ds_write2st64_b32 v1, v2, v3 offset0:124 offset1:126
	ds_read2st64_b32 v[2:3], v1 offset0:128 offset1:130
	s_waitcnt lgkmcnt(0)
	v_add_f32_e32 v2, v4, v2
	v_add_f32_e32 v3, v4, v3
	ds_write2st64_b32 v1, v2, v3 offset0:128 offset1:130
	ds_read2st64_b32 v[2:3], v1 offset0:132 offset1:134
	s_waitcnt lgkmcnt(0)
	v_add_f32_e32 v2, v4, v2
	v_add_f32_e32 v3, v4, v3
	ds_write2st64_b32 v1, v2, v3 offset0:132 offset1:134
	ds_read2st64_b32 v[2:3], v1 offset0:136 offset1:138
	s_waitcnt lgkmcnt(0)
	v_add_f32_e32 v2, v4, v2
	v_add_f32_e32 v3, v4, v3
	ds_write2st64_b32 v1, v2, v3 offset0:136 offset1:138
	ds_read2st64_b32 v[2:3], v1 offset0:140 offset1:142
	s_waitcnt lgkmcnt(0)
	v_add_f32_e32 v2, v4, v2
	v_add_f32_e32 v3, v4, v3
	ds_write2st64_b32 v1, v2, v3 offset0:140 offset1:142

	.amdhsa_kernel _Z14fwd_megakernel6Params
		.amdhsa_group_segment_fixed_size 74768
		.amdhsa_private_segment_fixed_size 0
		.amdhsa_kernarg_size 464
		.amdhsa_user_sgpr_count 2
		.amdhsa_user_sgpr_dispatch_ptr 0
		.amdhsa_user_sgpr_queue_ptr 0
		.amdhsa_user_sgpr_kernarg_segment_ptr 1
		.amdhsa_user_sgpr_dispatch_id 0
		.amdhsa_user_sgpr_kernarg_preload_length 0
		.amdhsa_user_sgpr_kernarg_preload_offset 0
		.amdhsa_user_sgpr_private_segment_size 0
		.amdhsa_uses_dynamic_stack 0
		.amdhsa_enable_private_segment 0
		.amdhsa_system_sgpr_workgroup_id_x 1
		.amdhsa_system_sgpr_workgroup_id_y 0
		.amdhsa_system_sgpr_workgroup_id_z 0
		.amdhsa_system_sgpr_workgroup_info 0
		.amdhsa_system_vgpr_workitem_id 2
		.amdhsa_next_free_vgpr 253
		.amdhsa_next_free_sgpr 102
		.amdhsa_accum_offset 256
		.amdhsa_reserve_vcc 1
		.amdhsa_float_round_mode_32 0
		.amdhsa_float_round_mode_16_64 0
		.amdhsa_float_denorm_mode_32 3
		.amdhsa_float_denorm_mode_16_64 3
		.amdhsa_dx10_clamp 1
		.amdhsa_ieee_mode 1
		.amdhsa_fp16_overflow 0
		.amdhsa_tg_split 0
		.amdhsa_exception_fp_ieee_invalid_op 0
		.amdhsa_exception_fp_denorm_src 0
		.amdhsa_exception_fp_ieee_div_zero 0
		.amdhsa_exception_fp_ieee_overflow 0
		.amdhsa_exception_fp_ieee_underflow 0
		.amdhsa_exception_fp_ieee_inexact 0
		.amdhsa_exception_int_div_zero 0
	.end_amdhsa_kernel

amdhsa.kernels:
  - .agpr_count:     0
    .args:
      - .offset:         0
        .size:           208
        .value_kind:     by_value
      - .offset:         208
        .size:           4
        .value_kind:     hidden_block_count_x
      - .offset:         212
        .size:           4
        .value_kind:     hidden_block_count_y
      - .offset:         216
        .size:           4
        .value_kind:     hidden_block_count_z
      - .offset:         220
        .size:           2
        .value_kind:     hidden_group_size_x
      - .offset:         222
        .size:           2
        .value_kind:     hidden_group_size_y
      - .offset:         224
        .size:           2
        .value_kind:     hidden_group_size_z
      - .offset:         226
        .size:           2
        .value_kind:     hidden_remainder_x
      - .offset:         228
        .size:           2
        .value_kind:     hidden_remainder_y
      - .offset:         230
        .size:           2
        .value_kind:     hidden_remainder_z
      - .offset:         248
        .size:           8
        .value_kind:     hidden_global_offset_x
      - .offset:         256
        .size:           8
        .value_kind:     hidden_global_offset_y
      - .offset:         264
        .size:           8
        .value_kind:     hidden_global_offset_z
      - .offset:         272
        .size:           2
        .value_kind:     hidden_grid_dims
      - .offset:         296
        .size:           8
        .value_kind:     hidden_multigrid_sync_arg
    .group_segment_fixed_size: 74768
    .kernarg_segment_align: 8
    .kernarg_segment_size: 464
    .language:       OpenCL C
    .language_version:
      - 2
      - 0
    .max_flat_workgroup_size: 256
    .name:           _Z14fwd_megakernel6Params
    .private_segment_fixed_size: 0
    .sgpr_count:     108
    .sgpr_spill_count: 307
    .symbol:         _Z14fwd_megakernel6Params.kd
    .uniform_work_group_size: 1
    .uses_dynamic_stack: false
    .vgpr_count:     253
    .vgpr_spill_count: 0
    .wavefront_size: 64
